# v52: v46 with faster flag polling (s_sleep 1) in the rwkv scan hand-off spin loops
# speedup vs baseline: 1.0064x; 1.0064x over previous
.LBB0_3006:
	s_sleep 1
	s_cbranch_execz .LBB0_3011

.LBB0_3021:
	s_add_i32 s19, s19, 1
	s_cmp_gt_u32 s19, 0x400000
	s_cbranch_scc1 .LBB0_3018
	s_mov_b64 s[4:5], -1
	s_sleep 1
	s_branch .LBB0_3018
